# LMD: differential-attention lambda scalars computed in the in-proj slack of layer 0 by one wave instead of two threads of workgroup 0 in the prologue
# speedup vs baseline: 1.0174x; 1.0011x over previous
.LBB0_17:
	s_load_dwordx16 s[12:27], s[0:1], 0x0
	v_mov_b32_e32 v6, v156
	s_mov_b32 s75, 0
	s_load_dword s60, s[0:1], 0xa0
	s_waitcnt lgkmcnt(0)
	v_writelane_b32 v234, s12, 2
	s_lshl_b64 s[10:11], s[74:75], 8
	v_ashrrev_i32_e32 v7, 31, v6
	v_writelane_b32 v234, s13, 3
	v_writelane_b32 v234, s14, 4
	v_writelane_b32 v234, s15, 5
	v_writelane_b32 v234, s16, 6
	v_writelane_b32 v234, s17, 7
	v_writelane_b32 v234, s18, 8
	v_writelane_b32 v234, s19, 9
	v_writelane_b32 v234, s20, 10
	v_writelane_b32 v234, s21, 11
	v_writelane_b32 v234, s22, 12
	v_writelane_b32 v234, s23, 13
	v_writelane_b32 v234, s24, 14
	v_writelane_b32 v234, s25, 15
	v_writelane_b32 v234, s26, 16
	v_writelane_b32 v234, s27, 17
	s_load_dwordx16 s[16:31], s[0:1], 0x40
	s_add_u32 s0, s0, 0xa0
	v_lshl_add_u64 v[4:5], s[10:11], 0, v[6:7]
	s_addc_u32 s1, s1, 0
	v_writelane_b32 v234, s0, 18
	v_cmp_gt_i64_e32 vcc, 0, v[4:5]
	s_nop 0
	v_writelane_b32 v234, s1, 19
	s_and_saveexec_b64 s[0:1], vcc
	s_cbranch_execz .LBB0_19
	v_lshlrev_b32_e32 v0, 5, v4
	v_ashrrev_i32_e32 v1, 31, v0
	v_lshlrev_b64 v[16:17], 2, v[0:1]
	s_waitcnt lgkmcnt(0)
	v_lshl_add_u64 v[116:117], s[18:19], 0, v[16:17]
	v_lshl_add_u64 v[120:121], s[20:21], 0, v[16:17]
	global_load_dwordx4 v[0:3], v[116:117], off
	global_load_dwordx4 v[8:11], v[120:121], off
	v_lshl_add_u64 v[124:125], s[22:23], 0, v[16:17]
	global_load_dwordx4 v[12:15], v[124:125], off
	v_lshl_add_u64 v[128:129], s[24:25], 0, v[16:17]
	global_load_dwordx4 v[16:19], v[128:129], off
	global_load_dwordx4 v[20:23], v[116:117], off offset:16
	global_load_dwordx4 v[24:27], v[120:121], off offset:16
	global_load_dwordx4 v[28:31], v[124:125], off offset:16
	global_load_dwordx4 v[32:35], v[128:129], off offset:16
	global_load_dwordx4 v[36:39], v[116:117], off offset:32
	global_load_dwordx4 v[40:43], v[120:121], off offset:32
	global_load_dwordx4 v[44:47], v[124:125], off offset:32
	global_load_dwordx4 v[48:51], v[128:129], off offset:32
	global_load_dwordx4 v[52:55], v[116:117], off offset:48
	global_load_dwordx4 v[56:59], v[120:121], off offset:48
	global_load_dwordx4 v[60:63], v[124:125], off offset:48
	global_load_dwordx4 v[64:67], v[128:129], off offset:48
	global_load_dwordx4 v[68:71], v[116:117], off offset:64
	global_load_dwordx4 v[72:75], v[120:121], off offset:64
	global_load_dwordx4 v[76:79], v[124:125], off offset:64
	global_load_dwordx4 v[80:83], v[128:129], off offset:64
	global_load_dwordx4 v[84:87], v[116:117], off offset:80
	global_load_dwordx4 v[88:91], v[120:121], off offset:80
	global_load_dwordx4 v[92:95], v[124:125], off offset:80
	global_load_dwordx4 v[96:99], v[128:129], off offset:80
	global_load_dwordx4 v[100:103], v[116:117], off offset:96
	global_load_dwordx4 v[104:107], v[120:121], off offset:96
	global_load_dwordx4 v[108:111], v[124:125], off offset:96
	global_load_dwordx4 v[112:115], v[128:129], off offset:96
	s_nop 0
	global_load_dwordx4 v[116:119], v[116:117], off offset:112
	s_nop 0
	global_load_dwordx4 v[120:123], v[120:121], off offset:112
	s_nop 0
	global_load_dwordx4 v[124:127], v[124:125], off offset:112
	s_nop 0
	global_load_dwordx4 v[128:131], v[128:129], off offset:112
	v_xor_b32_e32 v133, v4, v5
	v_ffbh_i32_e32 v132, v5
	v_ashrrev_i32_e32 v133, 31, v133
	v_add_u32_e32 v132, -1, v132
	v_add_u32_e32 v133, 32, v133
	v_min_u32_e32 v134, v132, v133
	v_lshlrev_b64 v[132:133], v134, v[4:5]
	v_min_u32_e32 v132, 1, v132
	v_or_b32_e32 v132, v133, v132
	v_cvt_f32_i32_e32 v133, v132
	v_sub_u32_e32 v134, 32, v134
	s_mov_b32 s6, 0x3fb8aa3b
	s_mov_b32 s7, 0xc2ce8ed0
	v_ldexp_f32 v133, v133, v134
	v_mul_f32_e32 v133, 0xbe99999a, v133
	v_cmp_ngt_f32_e32 vcc, s7, v133
	s_mov_b32 s12, 0x42b17218
	v_mov_b32_e32 v132, 0
	s_waitcnt vmcnt(30)
	v_fma_f32 v0, v0, v8, 0
	v_fmac_f32_e32 v0, v1, v9
	v_fmac_f32_e32 v0, v2, v10
	v_fmac_f32_e32 v0, v3, v11
	s_waitcnt vmcnt(26)
	v_fmac_f32_e32 v0, v20, v24
	v_fmac_f32_e32 v0, v21, v25
	v_fmac_f32_e32 v0, v22, v26
	v_fmac_f32_e32 v0, v23, v27
	v_fma_f32 v8, v12, v16, 0
	s_waitcnt vmcnt(22)
	v_fmac_f32_e32 v0, v36, v40
	v_fmac_f32_e32 v8, v13, v17
	v_fmac_f32_e32 v0, v37, v41
	v_fmac_f32_e32 v8, v14, v18
	v_fmac_f32_e32 v0, v38, v42
	v_fmac_f32_e32 v8, v15, v19
	v_fmac_f32_e32 v0, v39, v43
	v_fmac_f32_e32 v8, v28, v32
	s_waitcnt vmcnt(18)
	v_fmac_f32_e32 v0, v52, v56
	v_fmac_f32_e32 v8, v29, v33
	v_fmac_f32_e32 v0, v53, v57
	v_fmac_f32_e32 v8, v30, v34
	v_fmac_f32_e32 v0, v54, v58
	v_fmac_f32_e32 v8, v31, v35
	v_fmac_f32_e32 v0, v55, v59
	v_fmac_f32_e32 v8, v44, v48
	s_waitcnt vmcnt(14)
	v_fmac_f32_e32 v0, v68, v72
	v_fmac_f32_e32 v8, v45, v49
	v_fmac_f32_e32 v0, v69, v73
	v_fmac_f32_e32 v8, v46, v50
	v_fmac_f32_e32 v0, v70, v74
	v_fmac_f32_e32 v8, v47, v51
	v_fmac_f32_e32 v0, v71, v75
	v_fmac_f32_e32 v8, v60, v64
	s_waitcnt vmcnt(10)
	v_fmac_f32_e32 v0, v84, v88
	v_fmac_f32_e32 v8, v61, v65
	v_fmac_f32_e32 v0, v85, v89
	v_fmac_f32_e32 v8, v62, v66
	v_fmac_f32_e32 v0, v86, v90
	v_fmac_f32_e32 v8, v63, v67
	v_fmac_f32_e32 v0, v87, v91
	v_fmac_f32_e32 v8, v76, v80
	s_waitcnt vmcnt(6)
	v_fmac_f32_e32 v0, v100, v104
	v_fmac_f32_e32 v8, v77, v81
	v_fmac_f32_e32 v0, v101, v105
	v_fmac_f32_e32 v8, v78, v82
	v_fmac_f32_e32 v0, v102, v106
	v_fmac_f32_e32 v8, v79, v83
	v_fmac_f32_e32 v0, v103, v107
	v_fmac_f32_e32 v8, v92, v96
	s_waitcnt vmcnt(2)
	v_fmac_f32_e32 v0, v116, v120
	v_fmac_f32_e32 v8, v93, v97
	v_fmac_f32_e32 v0, v117, v121
	v_mul_f32_e32 v1, 0x3fb8aa3b, v133
	v_fmac_f32_e32 v8, v94, v98
	v_fmac_f32_e32 v0, v118, v122
	v_fma_f32 v2, v133, s6, -v1
	v_rndne_f32_e32 v3, v1
	v_fmac_f32_e32 v8, v95, v99
	v_fmac_f32_e32 v2, 0x32a5705f, v133
	v_sub_f32_e32 v1, v1, v3
	v_fmac_f32_e32 v0, v119, v123
	v_fmac_f32_e32 v8, v108, v112
	v_add_f32_e32 v1, v1, v2
	v_cvt_i32_f32_e32 v2, v3
	v_mul_f32_e32 v3, 0x3fb8aa3b, v0
	v_fmac_f32_e32 v8, v109, v113
	v_exp_f32_e32 v1, v1
	v_fma_f32 v9, v0, s6, -v3
	v_rndne_f32_e32 v10, v3
	v_fmac_f32_e32 v8, v110, v114
	v_fmac_f32_e32 v9, 0x32a5705f, v0
	v_sub_f32_e32 v3, v3, v10
	v_fmac_f32_e32 v8, v111, v115
	v_add_f32_e32 v3, v3, v9
	s_waitcnt vmcnt(0)
	v_fmac_f32_e32 v8, v124, v128
	v_exp_f32_e32 v3, v3
	v_cvt_i32_f32_e32 v9, v10
	v_fmac_f32_e32 v8, v125, v129
	v_ldexp_f32 v1, v1, v2
	v_fmac_f32_e32 v8, v126, v130
	v_cndmask_b32_e32 v1, 0, v1, vcc
	v_mov_b32_e32 v2, 0x7f800000
	v_cmp_nlt_f32_e32 vcc, s12, v133
	v_fmac_f32_e32 v8, v127, v131
	v_mov_b32_e32 v10, 0x3f4ccccd
	v_cndmask_b32_e32 v1, v2, v1, vcc
	v_fmac_f32_e32 v10, 0xbf19999a, v1
	v_ldexp_f32 v1, v3, v9
	v_mul_f32_e32 v3, 0x3fb8aa3b, v8
	v_fma_f32 v9, v8, s6, -v3
	v_rndne_f32_e32 v11, v3
	v_fmac_f32_e32 v9, 0x32a5705f, v8
	v_sub_f32_e32 v3, v3, v11
	v_add_f32_e32 v3, v3, v9
	v_exp_f32_e32 v3, v3
	v_cvt_i32_f32_e32 v9, v11
	v_cmp_ngt_f32_e32 vcc, s7, v0
	s_add_u32 s6, s80, 0x1000
	v_add_u32_e32 v133, 2, v4
	v_cndmask_b32_e32 v1, 0, v1, vcc
	v_cmp_nlt_f32_e32 vcc, s12, v0
	s_nop 1
	v_cndmask_b32_e32 v0, v2, v1, vcc
	v_ldexp_f32 v1, v3, v9
	v_cmp_ngt_f32_e32 vcc, s7, v8
	s_addc_u32 s7, s81, 0
	s_nop 0
	v_cndmask_b32_e32 v1, 0, v1, vcc
	v_cmp_nlt_f32_e32 vcc, s12, v8
	s_nop 1
	v_cndmask_b32_e32 v1, v2, v1, vcc
	v_sub_f32_e32 v0, v0, v1
	v_add_f32_e32 v2, v10, v0
	v_lshl_add_u64 v[0:1], v[4:5], 2, s[6:7]
	global_store_dword v[0:1], v2, off
	v_ashrrev_i64 v[0:1], 30, v[132:133]
	v_lshl_add_u64 v[0:1], s[6:7], 0, v[0:1]
	global_store_dword v[0:1], v10, off

.LBB0_587:
	s_cmp_lt_u32 s50, 56
	s_cbranch_scc1 .Lwd_skip
	s_lshr_b32 s5, s52, 4
	s_lshl_b32 s5, s5, 3
	s_add_u32 s5, s5, s50
	s_sub_u32 s5, s5, 56
	s_cmp_lg_u32 s2, 0
	s_cbranch_scc1 .Lwd_done
	s_cmp_lg_u32 s5, 0
	s_cbranch_scc1 .Llm_skip
	v_cmp_gt_u32_e32 vcc, 64, v156
	s_and_saveexec_b64 s[6:7], vcc
	s_cbranch_execz .Llm_end
	v_readlane_b32 s12, v234, 22
	v_readlane_b32 s13, v234, 23
	v_readlane_b32 s14, v234, 24
	v_readlane_b32 s15, v234, 25
	v_readlane_b32 s16, v234, 26
	v_readlane_b32 s17, v234, 27
	v_readlane_b32 s8, v234, 28
	v_readlane_b32 s9, v234, 29
	v_lshlrev_b32_e32 v2, 2, v156
	s_nop 3
	global_load_dword v3, v2, s[12:13]
	global_load_dword v8, v2, s[14:15]
	global_load_dword v9, v2, s[16:17]
	global_load_dword v10, v2, s[8:9]
	s_waitcnt vmcnt(0)
	v_mul_f32_e32 v3, v3, v8
	v_mul_f32_e32 v9, v9, v10
	s_nop 1
	v_add_f32_dpp v3, v3, v3 quad_perm:[1,0,3,2] row_mask:0xf bank_mask:0xf
	s_nop 1
	v_add_f32_dpp v3, v3, v3 quad_perm:[2,3,0,1] row_mask:0xf bank_mask:0xf
	s_nop 1
	v_add_f32_dpp v3, v3, v3 row_half_mirror row_mask:0xf bank_mask:0xf
	s_nop 1
	v_add_f32_dpp v3, v3, v3 row_mirror row_mask:0xf bank_mask:0xf
	s_nop 1
	v_add_f32_dpp v9, v9, v9 quad_perm:[1,0,3,2] row_mask:0xf bank_mask:0xf
	s_nop 1
	v_add_f32_dpp v9, v9, v9 quad_perm:[2,3,0,1] row_mask:0xf bank_mask:0xf
	s_nop 1
	v_add_f32_dpp v9, v9, v9 row_half_mirror row_mask:0xf bank_mask:0xf
	s_nop 1
	v_add_f32_dpp v9, v9, v9 row_mirror row_mask:0xf bank_mask:0xf
	s_nop 1
	v_readlane_b32 s12, v3, 0
	v_readlane_b32 s13, v3, 16
	v_readlane_b32 s14, v3, 32
	v_readlane_b32 s15, v3, 48
	v_readlane_b32 s16, v9, 0
	v_readlane_b32 s17, v9, 16
	v_readlane_b32 s8, v9, 32
	v_readlane_b32 s9, v9, 48
	s_add_u32 s0, s80, 0x1000
	s_addc_u32 s1, s81, 0
	v_mov_b32_e32 v12, 0
	s_nop 1
	v_mov_b32_e32 v2, s12
	v_add_f32_e32 v2, s13, v2
	v_mov_b32_e32 v3, s16
	v_add_f32_e32 v3, s17, v3
	v_mul_f32_e32 v2, 0x3fb8aa3b, v2
	v_mul_f32_e32 v3, 0x3fb8aa3b, v3
	v_exp_f32_e32 v2, v2
	v_exp_f32_e32 v3, v3
	s_nop 0
	v_sub_f32_e32 v2, v2, v3
	v_add_f32_e32 v2, 0x3e4ccccc, v2
	v_mov_b32_e32 v3, 0x3e4ccccc
	global_store_dword v12, v2, s[0:1] offset:0
	global_store_dword v12, v3, s[0:1] offset:8
	v_mov_b32_e32 v2, s14
	v_add_f32_e32 v2, s15, v2
	v_mov_b32_e32 v3, s8
	v_add_f32_e32 v3, s9, v3
	v_mul_f32_e32 v2, 0x3fb8aa3b, v2
	v_mul_f32_e32 v3, 0x3fb8aa3b, v3
	v_exp_f32_e32 v2, v2
	v_exp_f32_e32 v3, v3
	s_nop 0
	v_sub_f32_e32 v2, v2, v3
	v_add_f32_e32 v2, 0x3eb60549, v2
	v_mov_b32_e32 v3, 0x3eb60549
	global_store_dword v12, v2, s[0:1] offset:4
	global_store_dword v12, v3, s[0:1] offset:12

.Llm_skip:
	v_readlane_b32 s12, v234, 4
	v_readlane_b32 s13, v234, 5
	s_add_u32 s0, s80, 0x400000
	s_addc_u32 s1, s81, 0
	s_lshr_b32 s5, s52, 4
	s_lshl_b32 s5, s5, 3
	s_add_u32 s5, s5, s50
	s_sub_u32 s5, s5, 56
	s_lshl_b32 s6, s5, 8
	v_add_u32_e32 v18, s6, v156
	v_add_u32_e32 v18, 0x1f000, v18
	v_mov_b32_e32 v101, 0x8421100
	v_mov_b32_e32 v102, 0x300
	s_mov_b32 s4, 0
